# v069 + weight-conversion phase draws 80 items per workgroup (10 per wave) instead of 64: one round covers all 16608 items, no second-round tail
# baseline (speedup 1.0000x reference)
;     __device__ __forceinline__ unsigned char* ws() const { return *(const __attribute__((address_space(4))) ucptr_t*)(p + 264); }
; __device__ __forceinline__ void phase_prep(const KA& A, const Ctx& F) {
;     float* scr = (float*)(F.lds + F.wave * 16384);
;     constexpr int NM = 13;
;     constexpr int cnt[NM] = {16 * 184, 6 * 32, 6 * 32, 4 * 32, 16 * 32, 16 * 88, 16 * 88, 44 * 32, 4 * 8, 4 * 8, 12, 12, 24};
;     constexpr int per_layer = cnt[0] + cnt[1] + cnt[2] + cnt[3] + cnt[4] + cnt[5] + cnt[6] + cnt[7] + cnt[8] + cnt[9] + cnt[10] + cnt[11] + cnt[12];
;     unsigned* ctr = (unsigned*)(F.ws + WS_CTL) + CW_PREP; volatile unsigned* slot = (volatile unsigned*)(F.lds + MISC_OFF + 68);
;     for (;;) {
;         __syncthreads();
;         if (F.tid == 0) *slot = __hip_atomic_fetch_add(ctr, 64u, __ATOMIC_RELAXED, __HIP_MEMORY_SCOPE_AGENT);
;         __syncthreads();
;         const int base = (int)*slot;
;         if (base >= DEPTH * per_layer) break;
; #pragma unroll 1
;       for (int sub = 0; sub < 8; ++sub) {
;         const int it = base + F.wave * 8 + sub;
.LBB0_61:
	v_mov_b32_e32 v4, v242
	s_barrier
	v_mov_b32_e32 v7, v81
	v_readfirstlane_b32 s2, v4
	s_ashr_i32 s4, s2, 6
	v_lshlrev_b32_e32 v0, 2, v4
	s_lshl_b32 s2, s4, 14
	v_bfe_u32 v1, v4, 3, 3
	v_and_b32_e32 v0, 28, v0
	s_add_i32 s5, s2, 0
	v_mul_u32_u24_e32 v2, 0x84, v1
	v_lshlrev_b32_e32 v3, 2, v0
	v_lshlrev_b32_e32 v14, 3, v4
	v_cmp_eq_u32_e64 s[2:3], 0, v4
	v_add3_u32 v3, s5, v2, v3
	v_and_b32_e32 v2, 56, v14
	v_lshlrev_b32_e32 v4, 5, v4
	v_mul_u32_u24_e32 v5, 0x84, v2
	v_and_b32_e32 v32, 32, v4
	v_lshlrev_b32_e32 v4, 2, v1
	s_mul_i32 s33, s4, 10
	v_or_b32_e32 v18, 8, v1
	v_or_b32_e32 v20, 16, v1
	v_or_b32_e32 v22, 24, v1
	v_add3_u32 v33, s5, v5, v4
	v_mul_u32_u24_e32 v4, 0x600, v1
	s_movk_i32 s4, 0x600
	v_add_u32_e32 v19, 0x420, v3
	v_add_u32_e32 v21, 0x840, v3
	v_add_u32_e32 v23, 0xc60, v3
	v_or_b32_e32 v24, 32, v1
	v_add_u32_e32 v25, 0x1080, v3
	v_or_b32_e32 v26, 40, v1
	v_add_u32_e32 v27, 0x14a0, v3
	v_or_b32_e32 v28, 48, v1
	v_add_u32_e32 v29, 0x18c0, v3
	v_or_b32_e32 v30, 56, v1
	v_add_u32_e32 v31, 0x1ce0, v3
	v_or_b32_e32 v34, v32, v1
	v_or_b32_e32 v35, v18, v32
	v_or_b32_e32 v36, v20, v32
	v_or_b32_e32 v37, v22, v32
	v_mov_b32_e32 v5, v81
	v_or_b32_e32 v6, 0xc000, v4
	v_mad_u32_u24 v8, v1, s4, v227
	v_mov_b32_e32 v9, v81
	v_mad_u32_u24 v10, v1, s4, v224
	v_mov_b32_e32 v11, v81
	v_mad_u32_u24 v12, v1, s4, v225
	v_mov_b32_e32 v13, v81
	v_bfe_u32 v38, v14, 4, 2
	s_mov_b64 s[4:5], 0
	s_branch .LBB0_64

; __device__ __forceinline__ void phase_prep(const KA& A, const Ctx& F) {
;     ...
;     for (;;) {
;         __syncthreads();
;         if (F.tid == 0) *slot = __hip_atomic_fetch_add(ctr, 64u, __ATOMIC_RELAXED, __HIP_MEMORY_SCOPE_AGENT);
;         __syncthreads();
;         const int base = (int)*slot;
;         if (base >= DEPTH * per_layer) break;
.LBB0_64:
	s_barrier
	s_and_saveexec_b64 s[6:7], s[2:3]
	s_cbranch_execz .LBB0_68
	s_mov_b64 s[10:11], exec
	v_mbcnt_lo_u32_b32 v14, s10, 0
	v_mbcnt_hi_u32_b32 v14, s11, v14
	v_cmp_eq_u32_e32 vcc, 0, v14
	s_and_saveexec_b64 s[8:9], vcc
	s_cbranch_execz .LBB0_67
	s_bcnt1_i32_b64 s10, s[10:11]
	s_mul_i32 s10, s10, 80
	v_readlane_b32 s12, v253, 60
	v_mov_b32_e32 v15, s10
	v_readlane_b32 s14, v253, 62
	v_readlane_b32 s15, v253, 63
	v_readlane_b32 s13, v253, 61
	s_nop 3
	global_atomic_add v15, v81, v15, s[14:15] offset:2048 sc0

; __device__ __forceinline__ void phase_prep(const KA& A, const Ctx& F) {
;     ...
;       for (int sub = 0; sub < 8; ++sub) {
;         const int it = base + F.wave * 8 + sub;
;         if (it >= DEPTH * per_layer) break;
.LBB0_121:
	s_or_b64 exec, exec, s[10:11]
	v_cmp_gt_i32_e32 vcc, 6, v40
	s_mov_b64 s[10:11], -1
	s_mov_b64 s[12:13], -1
	s_and_saveexec_b64 s[14:15], vcc
	v_cmp_eq_u32_e32 vcc, 0, v40
	s_orn2_b64 s[12:13], vcc, exec
	s_or_b64 exec, exec, s[14:15]
	s_and_saveexec_b64 s[14:15], s[12:13]
	s_xor_b64 s[12:13], exec, s[14:15]
	s_cbranch_execz .LBB0_70
	s_add_i32 s46, s46, 1
	s_cmp_eq_u32 s46, 10
	s_cselect_b64 s[10:11], -1, 0
	s_orn2_b64 s[10:11], s[10:11], exec
	s_branch .LBB0_70
